# work-queue preference: XCDs 0,3,6 plus the first 16 workgroups of XCD 1 (112 workgroups) start on the FoX queue (v104 had 96)
# speedup vs baseline: 1.0038x; 1.0038x over previous
; #define LAS __attribute__((address_space(3)))
;     LAS int* sitem = (LAS int*)(lds + ITEM_OFF);
;     constexpr int N_D = 256, N_B = 2048, N_A = 128, N_C = 128, N_ALL = N_D + N_B + N_A + N_C;
;     const int pref = ((__builtin_amdgcn_s_getreg((3 << 11) | 20) & 3u) != 0u) ? 1 : 0;
;     auto fetch = [&]() -> int {
;         auto q1 = [&](int i) -> int { return i < N_A + N_C ? N_D + N_B + i : N_D + (i - (N_A + N_C)); };
;         if (pref == 0) { int i = (int)atomicAdd(ctr, 1u); if (i < N_D) return i; i = (int)atomicAdd(ctr + 32, 1u); return i < N_ALL - N_D ? q1(i) : N_ALL; }
;         int i = (int)atomicAdd(ctr + 32, 1u); if (i < N_ALL - N_D) return q1(i); i = (int)atomicAdd(ctr, 1u); return i < N_D ? i : N_ALL; };
;     int nxt = 0;
;     if (threadIdx.x == 0) nxt = fetch();
.LBB0_112:
	v_readlane_b32 s0, v253, 49
	v_readlane_b32 s1, v253, 50
	s_lshl_b32 s0, s0, 1
	v_readlane_b32 s1, v253, 51
	s_add_i32 s0, s0, s1
	s_ashr_i32 s1, s0, 31
	v_readlane_b32 s20, v251, 1
	s_lshl_b64 s[0:1], s[0:1], 2
	v_readlane_b32 s22, v251, 3
	v_readlane_b32 s23, v251, 4
	s_add_u32 s0, s22, s0
	s_addc_u32 s1, s23, s1
	v_writelane_b32 v253, s0, 55
	v_mov_b32_e32 v180, 0
	v_readlane_b32 s21, v251, 2
	v_writelane_b32 v253, s1, 56
	s_getreg_b32 s0, hwreg(HW_REG_XCC_ID, 0, 4)
	s_lshr_b32 s1, 0x49, s0
	s_and_b32 s1, s1, 1
	v_readlane_b32 vcc_lo, v251, 0
	s_lshr_b32 vcc_lo, vcc_lo, 3
	s_cmp_lt_u32 vcc_lo, 16
	s_cselect_b32 vcc_lo, 1, 0
	s_cmp_eq_u32 s0, 1
	s_cselect_b32 vcc_hi, 1, 0
	s_and_b32 vcc_lo, vcc_lo, vcc_hi
	s_or_b32 s0, s1, vcc_lo
	s_cmp_eq_u32 s0, 0
	s_cselect_b64 s[0:1], -1, 0
	v_writelane_b32 v253, s0, 57
	v_readlane_b32 s24, v251, 5
	v_readlane_b32 s25, v251, 6
	v_writelane_b32 v253, s1, 58
	v_readlane_b32 s26, v251, 7
	v_readlane_b32 s27, v251, 8
	s_mov_b64 s[0:1], exec
	v_readlane_b32 s20, v251, 13
	v_readlane_b32 s21, v251, 14
	s_and_b64 s[20:21], s[0:1], s[20:21]
	s_mov_b64 exec, s[20:21]
	s_cbranch_execz .LBB0_131
	v_readlane_b32 s20, v253, 57
	v_readlane_b32 s21, v253, 58
	s_and_b64 vcc, exec, s[20:21]
	s_cbranch_vccz .LBB0_123
	s_mov_b64 s[22:23], exec
	v_mbcnt_lo_u32_b32 v0, s22, 0
	v_mbcnt_hi_u32_b32 v0, s23, v0
	v_cmp_eq_u32_e32 vcc, 0, v0
	s_and_saveexec_b64 s[20:21], vcc
	s_cbranch_execz .LBB0_116
	s_bcnt1_i32_b64 s22, s[22:23]
	v_mov_b32_e32 v2, s22
	v_readlane_b32 s22, v253, 55
	v_readlane_b32 s23, v253, 56
	s_nop 4
	global_atomic_add v2, v1, v2, s[22:23] offset:128 sc0
